# in-loop copy also in P7 K loop (covers the former P5 epilogue copy share), P5 second-round units split 4-way along K
# baseline (speedup 1.0000x reference)
.LBB0_661:
	s_lshl_b32 s64, s88, 11
	v_or_b32_e32 v0, s64, v222
	s_cmp_gt_i32 s88, 3
	v_add_u32_e32 v0, 0x31e800, v0
	s_mov_b32 s2, 0x32f800
	s_cselect_b64 s[0:1], -1, 0
	v_cmp_gt_i32_e32 vcc, s2, v0
	s_and_b64 s[2:3], s[0:1], vcc
	s_and_saveexec_b64 s[0:1], s[2:3]
	s_cbranch_execz .LBB0_664
	v_readlane_b32 s2, v247, 15
	v_add_u32_e32 v0, s64, v222
	s_add_i32 s6, s2, 0xffffe000
	v_add_u32_e32 v0, 0x31e800, v0
	s_mov_b64 s[2:3], 0
	s_mov_b32 s7, 0x80808081
	s_mov_b32 s8, 0xfffc0400
	s_movk_i32 s9, 0x4000
	s_mov_b32 s10, 0x32f7ff

.LBB0_1024:
	s_or_b64 exec, exec, s[0:1]
	v_lshlrev_b32_e32 v235, 4, v222
	s_mul_i32 s79, s88, 22
	s_mov_b32 s78, s79
	s_mov_b32 s79, 0
	s_mov_b32 s76, s79
	s_mov_b32 s79, s76
	s_min_u32 s79, s79, 21
	s_mov_b32 s80, s78
	s_add_i32 s79, s79, s80
	s_min_u32 s79, s79, 0x15ff
	s_lshr_b32 s80, s79, 1
	s_add_i32 s80, s80, 0xe04
	s_mul_i32 s81, s80, 0x8081
	s_lshr_b32 s81, s81, 24
	s_mul_i32 s90, s81, 0x1fe
	s_sub_i32 s80, s80, s90
	s_lshl_b32 s81, s81, 22
	s_lshl_b32 s80, s80, 13
	s_add_u32 s80, s80, s81
	s_bitcmp1_b32 s79, 0
	s_cselect_b32 s90, s84, s82
	s_cselect_b32 s91, s85, s83
	s_add_u32 s90, s90, s80
	s_addc_u32 s91, s91, 0
	s_add_u32 s90, s90, 0x4000
	s_addc_u32 s91, s91, 0
	global_load_dwordx4 v[240:243], v235, s[90:91] nt
	s_mov_b32 s79, 1
	s_mov_b32 s76, s79
	s_mov_b32 s98, 0
	s_mov_b32 s99, 0
	s_mov_b32 s100, 0
	s_mov_b32 s101, 40
	v_lshlrev_b32_e32 v244, 4, v222
	v_mov_b32_e32 v8, v222
	s_waitcnt lgkmcnt(0)
	s_barrier
	s_and_b64 vcc, exec, s[72:73]
	v_readfirstlane_b32 s6, v8
	v_readlane_b32 s3, v247, 18
	s_cbranch_vccnz .LBB0_1027
	s_cmp_gt_i32 s3, 3
	s_cbranch_scc0 .LBB0_1113
	s_lshl_b32 s0, s3, 5
	s_or_b32 s2, s0, 4
	s_cbranch_execz .LBB0_1114
	s_branch .LBB0_1115

.LBB0_1044:
	ds_read_b128 v[128:131], v230
	ds_read_b128 v[132:135], v230 offset:1024
	ds_read_b128 v[136:139], v230 offset:2048
	ds_read_b128 v[140:143], v230 offset:3072
	ds_read_b128 v[144:147], v231
	ds_read_b128 v[148:151], v231 offset:1024
	ds_read_b128 v[152:155], v231 offset:2048
	ds_read_b128 v[156:159], v231 offset:3072
	s_add_u32 s24, s2, 0x100
	s_addc_u32 s25, s3, 0
	s_cmp_eq_u32 s61, s101
	s_cselect_b32 s35, s7, s25
	s_cselect_b32 s34, s6, s24
	s_cselect_b32 s27, s19, s60
	s_cselect_b32 s26, s18, s59
	v_lshl_add_u64 v[208:209], s[2:3], 0, v[200:201]
	s_add_i32 m0, s36, 0xc000
	ds_read_b128 v[160:163], v232
	ds_read_b128 v[164:167], v232 offset:1024
	ds_read_b128 v[168:171], v232 offset:2048
	ds_read_b128 v[172:175], v232 offset:3072
	ds_read_b128 v[176:179], v232 offset:4096
	ds_read_b128 v[180:183], v232 offset:5120
	ds_read_b128 v[184:187], v232 offset:6144
	ds_read_b128 v[188:191], v232 offset:7168
	global_load_lds_dwordx4 v[208:209], off
	v_lshl_add_u64 v[208:209], s[2:3], 0, v[202:203]
	s_add_i32 m0, s36, 0xe000
	s_nop 0
	global_load_lds_dwordx4 v[208:209], off
	s_mov_b32 s79, s76
	s_add_i32 s79, s79, -1
	s_min_u32 s79, s79, 21
	s_mov_b32 s80, s78
	s_add_i32 s79, s79, s80
	s_min_u32 s79, s79, 0x15ff
	s_lshr_b32 s80, s79, 1
	s_add_i32 s80, s80, 0xe04
	s_mul_i32 s81, s80, 0x8081
	s_lshr_b32 s81, s81, 24
	s_mul_i32 s90, s81, 0x1fe
	s_sub_i32 s80, s80, s90
	s_lshl_b32 s81, s81, 22
	s_lshl_b32 s80, s80, 13
	s_add_u32 s80, s80, s81
	s_bitcmp1_b32 s79, 0
	s_cselect_b32 s90, s66, s70
	s_cselect_b32 s91, s67, s71
	s_add_u32 s90, s90, s80
	s_addc_u32 s91, s91, 0
	global_store_dwordx4 v235, v[240:243], s[90:91] nt
	s_mov_b32 s79, s76
	s_min_u32 s79, s79, 21
	s_mov_b32 s80, s78
	s_add_i32 s79, s79, s80
	s_min_u32 s79, s79, 0x15ff
	s_lshr_b32 s80, s79, 1
	s_add_i32 s80, s80, 0xe04
	s_mul_i32 s81, s80, 0x8081
	s_lshr_b32 s81, s81, 24
	s_mul_i32 s90, s81, 0x1fe
	s_sub_i32 s80, s80, s90
	s_lshl_b32 s81, s81, 22
	s_lshl_b32 s80, s80, 13
	s_add_u32 s80, s80, s81
	s_bitcmp1_b32 s79, 0
	s_cselect_b32 s90, s84, s82
	s_cselect_b32 s91, s85, s83
	s_add_u32 s90, s90, s80
	s_addc_u32 s91, s91, 0
	s_add_u32 s90, s90, 0x4000
	s_addc_u32 s91, s91, 0
	global_load_dwordx4 v[240:243], v235, s[90:91] nt
	s_mov_b32 s79, s76
	s_add_i32 s79, s79, 1
	s_mov_b32 s76, s79
	s_waitcnt vmcnt(10)
	s_waitcnt lgkmcnt(0)
	s_barrier
	s_setprio 1
	s_waitcnt lgkmcnt(0)
	v_mfma_f32_16x16x32_bf16 v[124:127], v[128:131], v[160:163], v[124:127]
	v_mfma_f32_16x16x32_bf16 v[120:123], v[136:139], v[160:163], v[120:123]
	v_mfma_f32_16x16x32_bf16 v[108:111], v[128:131], v[168:171], v[108:111]
	v_mfma_f32_16x16x32_bf16 v[104:107], v[136:139], v[168:171], v[104:107]
	v_mfma_f32_16x16x32_bf16 v[92:95], v[128:131], v[176:179], v[92:95]
	v_mfma_f32_16x16x32_bf16 v[88:91], v[136:139], v[176:179], v[88:91]
	v_mfma_f32_16x16x32_bf16 v[76:79], v[128:131], v[184:187], v[76:79]
	v_mfma_f32_16x16x32_bf16 v[72:75], v[136:139], v[184:187], v[72:75]
	v_mfma_f32_16x16x32_bf16 v[124:127], v[132:135], v[164:167], v[124:127]
	v_mfma_f32_16x16x32_bf16 v[120:123], v[140:143], v[164:167], v[120:123]
	v_mfma_f32_16x16x32_bf16 v[108:111], v[132:135], v[172:175], v[108:111]
	v_mfma_f32_16x16x32_bf16 v[104:107], v[140:143], v[172:175], v[104:107]
	v_mfma_f32_16x16x32_bf16 v[92:95], v[132:135], v[180:183], v[92:95]
	v_mfma_f32_16x16x32_bf16 v[88:91], v[140:143], v[180:183], v[88:91]
	v_mfma_f32_16x16x32_bf16 v[76:79], v[132:135], v[188:191], v[76:79]
	v_mfma_f32_16x16x32_bf16 v[72:75], v[140:143], v[188:191], v[72:75]
	s_setprio 0
	s_setprio 1
	v_mfma_f32_16x16x32_bf16 v[116:119], v[144:147], v[160:163], v[116:119]
	v_mfma_f32_16x16x32_bf16 v[112:115], v[152:155], v[160:163], v[112:115]
	v_mfma_f32_16x16x32_bf16 v[100:103], v[144:147], v[168:171], v[100:103]
	v_mfma_f32_16x16x32_bf16 v[96:99], v[152:155], v[168:171], v[96:99]
	v_mfma_f32_16x16x32_bf16 v[84:87], v[144:147], v[176:179], v[84:87]
	v_mfma_f32_16x16x32_bf16 v[80:83], v[152:155], v[176:179], v[80:83]
	v_mfma_f32_16x16x32_bf16 v[68:71], v[144:147], v[184:187], v[68:71]
	v_mfma_f32_16x16x32_bf16 v[64:67], v[152:155], v[184:187], v[64:67]
	v_mfma_f32_16x16x32_bf16 v[116:119], v[148:151], v[164:167], v[116:119]
	v_mfma_f32_16x16x32_bf16 v[112:115], v[156:159], v[164:167], v[112:115]
	v_mfma_f32_16x16x32_bf16 v[100:103], v[148:151], v[172:175], v[100:103]
	v_mfma_f32_16x16x32_bf16 v[96:99], v[156:159], v[172:175], v[96:99]
	v_mfma_f32_16x16x32_bf16 v[84:87], v[148:151], v[180:183], v[84:87]
	v_mfma_f32_16x16x32_bf16 v[80:83], v[156:159], v[180:183], v[80:83]
	v_mfma_f32_16x16x32_bf16 v[68:71], v[148:151], v[188:191], v[68:71]
	v_mfma_f32_16x16x32_bf16 v[64:67], v[156:159], v[188:191], v[64:67]
	s_setprio 0
	s_barrier
	s_add_i32 s2, s49, s33
	v_lshl_add_u64 v[208:209], s[26:27], 0, v[194:195]
	s_mov_b32 m0, s2
	ds_read_b128 v[160:163], v232 offset:16384
	ds_read_b128 v[164:167], v232 offset:17408
	ds_read_b128 v[168:171], v232 offset:18432
	ds_read_b128 v[172:175], v232 offset:19456
	ds_read_b128 v[176:179], v232 offset:20480
	ds_read_b128 v[180:183], v232 offset:21504
	ds_read_b128 v[184:187], v232 offset:22528
	ds_read_b128 v[188:191], v232 offset:23552
	global_load_lds_dwordx4 v[208:209], off
	s_add_i32 m0, s2, 0x2000
	s_add_u32 s2, s26, 0xb0000
	v_lshl_add_u64 v[210:211], s[26:27], 0, v[198:199]
	s_addc_u32 s3, s27, 0
	s_add_i32 s62, s50, s33
	global_load_lds_dwordx4 v[210:211], off
	v_lshl_add_u64 v[212:213], s[2:3], 0, v[194:195]
	s_mov_b32 m0, s62
	v_lshl_add_u64 v[214:215], s[34:35], 0, v[196:197]
	global_load_lds_dwordx4 v[212:213], off
	v_lshl_add_u64 v[212:213], s[2:3], 0, v[198:199]
	s_add_i32 m0, s62, 0x2000
	s_nop 0
	global_load_lds_dwordx4 v[212:213], off
	v_lshl_add_u64 v[212:213], s[34:35], 0, v[192:193]
	s_mov_b32 m0, s36
	s_nop 0
	global_load_lds_dwordx4 v[212:213], off
	s_mov_b32 m0, s37
	s_nop 0
	global_load_lds_dwordx4 v[214:215], off
	s_waitcnt vmcnt(10)
	s_waitcnt lgkmcnt(0)
	s_barrier
	s_setprio 1
	s_waitcnt lgkmcnt(0)
	v_mfma_f32_16x16x32_bf16 v[60:63], v[128:131], v[160:163], v[60:63]
	v_mfma_f32_16x16x32_bf16 v[56:59], v[136:139], v[160:163], v[56:59]
	v_mfma_f32_16x16x32_bf16 v[44:47], v[128:131], v[168:171], v[44:47]
	v_mfma_f32_16x16x32_bf16 v[40:43], v[136:139], v[168:171], v[40:43]
	v_mfma_f32_16x16x32_bf16 v[28:31], v[128:131], v[176:179], v[28:31]
	v_mfma_f32_16x16x32_bf16 v[24:27], v[136:139], v[176:179], v[24:27]
	v_mfma_f32_16x16x32_bf16 v[12:15], v[128:131], v[184:187], v[12:15]
	v_mfma_f32_16x16x32_bf16 v[8:11], v[136:139], v[184:187], v[8:11]
	v_mfma_f32_16x16x32_bf16 v[60:63], v[132:135], v[164:167], v[60:63]
	v_mfma_f32_16x16x32_bf16 v[56:59], v[140:143], v[164:167], v[56:59]
	v_mfma_f32_16x16x32_bf16 v[44:47], v[132:135], v[172:175], v[44:47]
	v_mfma_f32_16x16x32_bf16 v[40:43], v[140:143], v[172:175], v[40:43]
	v_mfma_f32_16x16x32_bf16 v[28:31], v[132:135], v[180:183], v[28:31]
	v_mfma_f32_16x16x32_bf16 v[24:27], v[140:143], v[180:183], v[24:27]
	v_mfma_f32_16x16x32_bf16 v[12:15], v[132:135], v[188:191], v[12:15]
	v_mfma_f32_16x16x32_bf16 v[8:11], v[140:143], v[188:191], v[8:11]
	s_setprio 0
	s_setprio 1
	v_mfma_f32_16x16x32_bf16 v[52:55], v[144:147], v[160:163], v[52:55]
	v_mfma_f32_16x16x32_bf16 v[48:51], v[152:155], v[160:163], v[48:51]
	v_mfma_f32_16x16x32_bf16 v[36:39], v[144:147], v[168:171], v[36:39]
	v_mfma_f32_16x16x32_bf16 v[32:35], v[152:155], v[168:171], v[32:35]
	v_mfma_f32_16x16x32_bf16 v[20:23], v[144:147], v[176:179], v[20:23]
	v_mfma_f32_16x16x32_bf16 v[16:19], v[152:155], v[176:179], v[16:19]
	v_mfma_f32_16x16x32_bf16 v[4:7], v[144:147], v[184:187], v[4:7]
	v_mfma_f32_16x16x32_bf16 v[0:3], v[152:155], v[184:187], v[0:3]
	v_mfma_f32_16x16x32_bf16 v[52:55], v[148:151], v[164:167], v[52:55]
	v_mfma_f32_16x16x32_bf16 v[48:51], v[156:159], v[164:167], v[48:51]
	v_mfma_f32_16x16x32_bf16 v[36:39], v[148:151], v[172:175], v[36:39]
	v_mfma_f32_16x16x32_bf16 v[32:35], v[156:159], v[172:175], v[32:35]
	v_mfma_f32_16x16x32_bf16 v[20:23], v[148:151], v[180:183], v[20:23]
	v_mfma_f32_16x16x32_bf16 v[16:19], v[156:159], v[180:183], v[16:19]
	v_mfma_f32_16x16x32_bf16 v[4:7], v[148:151], v[188:191], v[4:7]
	v_mfma_f32_16x16x32_bf16 v[0:3], v[156:159], v[188:191], v[0:3]
	s_setprio 0
	s_barrier
	s_add_i32 s62, 0, 0x18000
	s_add_i32 s63, 0, 0x1c000
	v_add_u32_e32 v140, s62, v228
	v_add_u32_e32 v156, s63, v228
	ds_read_b128 v[128:131], v140
	ds_read_b128 v[132:135], v140 offset:1024
	ds_read_b128 v[136:139], v140 offset:2048
	ds_read_b128 v[140:143], v140 offset:3072
	ds_read_b128 v[144:147], v156
	ds_read_b128 v[148:151], v156 offset:1024
	ds_read_b128 v[152:155], v156 offset:2048
	ds_read_b128 v[156:159], v156 offset:3072
	s_add_u32 s2, s34, 0xb0000
	s_addc_u32 s3, s35, 0
	s_mov_b32 m0, s38
	v_lshl_add_u64 v[216:217], s[2:3], 0, v[192:193]
	ds_read_b128 v[160:163], v232 offset:32768
	ds_read_b128 v[164:167], v232 offset:33792
	ds_read_b128 v[168:171], v232 offset:34816
	ds_read_b128 v[172:175], v232 offset:35840
	ds_read_b128 v[176:179], v232 offset:36864
	ds_read_b128 v[180:183], v232 offset:37888
	ds_read_b128 v[184:187], v232 offset:38912
	ds_read_b128 v[188:191], v232 offset:39936
	global_load_lds_dwordx4 v[216:217], off
	v_lshl_add_u64 v[216:217], s[2:3], 0, v[196:197]
	s_mov_b32 m0, s39
	s_nop 0
	global_load_lds_dwordx4 v[216:217], off
	s_waitcnt vmcnt(10)
	s_waitcnt lgkmcnt(0)
	s_barrier
	s_setprio 1
	s_waitcnt lgkmcnt(0)
	v_mfma_f32_16x16x32_bf16 v[124:127], v[128:131], v[160:163], v[124:127]
	v_mfma_f32_16x16x32_bf16 v[120:123], v[136:139], v[160:163], v[120:123]
	v_mfma_f32_16x16x32_bf16 v[108:111], v[128:131], v[168:171], v[108:111]
	v_mfma_f32_16x16x32_bf16 v[104:107], v[136:139], v[168:171], v[104:107]
	v_mfma_f32_16x16x32_bf16 v[92:95], v[128:131], v[176:179], v[92:95]
	v_mfma_f32_16x16x32_bf16 v[88:91], v[136:139], v[176:179], v[88:91]
	v_mfma_f32_16x16x32_bf16 v[76:79], v[128:131], v[184:187], v[76:79]
	v_mfma_f32_16x16x32_bf16 v[72:75], v[136:139], v[184:187], v[72:75]
	v_mfma_f32_16x16x32_bf16 v[124:127], v[132:135], v[164:167], v[124:127]
	v_mfma_f32_16x16x32_bf16 v[120:123], v[140:143], v[164:167], v[120:123]
	v_mfma_f32_16x16x32_bf16 v[108:111], v[132:135], v[172:175], v[108:111]
	v_mfma_f32_16x16x32_bf16 v[104:107], v[140:143], v[172:175], v[104:107]
	v_mfma_f32_16x16x32_bf16 v[92:95], v[132:135], v[180:183], v[92:95]
	v_mfma_f32_16x16x32_bf16 v[88:91], v[140:143], v[180:183], v[88:91]
	v_mfma_f32_16x16x32_bf16 v[76:79], v[132:135], v[188:191], v[76:79]
	v_mfma_f32_16x16x32_bf16 v[72:75], v[140:143], v[188:191], v[72:75]
	s_setprio 0
	s_setprio 1
	v_mfma_f32_16x16x32_bf16 v[116:119], v[144:147], v[160:163], v[116:119]
	v_mfma_f32_16x16x32_bf16 v[112:115], v[152:155], v[160:163], v[112:115]
	v_mfma_f32_16x16x32_bf16 v[100:103], v[144:147], v[168:171], v[100:103]
	v_mfma_f32_16x16x32_bf16 v[96:99], v[152:155], v[168:171], v[96:99]
	v_mfma_f32_16x16x32_bf16 v[84:87], v[144:147], v[176:179], v[84:87]
	v_mfma_f32_16x16x32_bf16 v[80:83], v[152:155], v[176:179], v[80:83]
	v_mfma_f32_16x16x32_bf16 v[68:71], v[144:147], v[184:187], v[68:71]
	v_mfma_f32_16x16x32_bf16 v[64:67], v[152:155], v[184:187], v[64:67]
	v_mfma_f32_16x16x32_bf16 v[116:119], v[148:151], v[164:167], v[116:119]
	v_mfma_f32_16x16x32_bf16 v[112:115], v[156:159], v[164:167], v[112:115]
	v_mfma_f32_16x16x32_bf16 v[100:103], v[148:151], v[172:175], v[100:103]
	v_mfma_f32_16x16x32_bf16 v[96:99], v[156:159], v[172:175], v[96:99]
	v_mfma_f32_16x16x32_bf16 v[84:87], v[148:151], v[180:183], v[84:87]
	v_mfma_f32_16x16x32_bf16 v[80:83], v[156:159], v[180:183], v[80:83]
	v_mfma_f32_16x16x32_bf16 v[68:71], v[148:151], v[188:191], v[68:71]
	v_mfma_f32_16x16x32_bf16 v[64:67], v[156:159], v[188:191], v[64:67]
	s_setprio 0
	s_barrier
	s_add_i32 s2, s62, s33
	v_lshl_add_u64 v[208:209], v[208:209], 0, s[12:13]
	s_mov_b32 m0, s2
	ds_read_b128 v[160:163], v232 offset:49152
	ds_read_b128 v[164:167], v232 offset:50176
	ds_read_b128 v[168:171], v232 offset:51200
	ds_read_b128 v[172:175], v232 offset:52224
	ds_read_b128 v[176:179], v232 offset:53248
	ds_read_b128 v[180:183], v232 offset:54272
	ds_read_b128 v[184:187], v232 offset:55296
	ds_read_b128 v[188:191], v232 offset:56320
	global_load_lds_dwordx4 v[208:209], off
	s_add_i32 m0, s2, 0x2000
	s_add_u32 s2, s26, 0xb0080
	v_lshl_add_u64 v[208:209], v[210:211], 0, s[12:13]
	s_addc_u32 s3, s27, 0
	s_add_i32 s26, s63, s33
	global_load_lds_dwordx4 v[208:209], off
	v_lshl_add_u64 v[208:209], s[2:3], 0, v[194:195]
	s_mov_b32 m0, s26
	s_nop 0
	global_load_lds_dwordx4 v[208:209], off
	v_lshl_add_u64 v[208:209], s[2:3], 0, v[198:199]
	s_add_i32 m0, s26, 0x2000
	s_nop 0
	global_load_lds_dwordx4 v[208:209], off
	v_lshl_add_u64 v[208:209], v[212:213], 0, s[12:13]
	s_mov_b32 m0, s46
	s_nop 0
	global_load_lds_dwordx4 v[208:209], off
	v_lshl_add_u64 v[208:209], v[214:215], 0, s[12:13]
	s_mov_b32 m0, s47
	s_nop 0
	global_load_lds_dwordx4 v[208:209], off
	s_waitcnt vmcnt(8)
	s_waitcnt lgkmcnt(0)
	s_barrier
	s_setprio 1
	s_waitcnt lgkmcnt(0)
	v_mfma_f32_16x16x32_bf16 v[60:63], v[128:131], v[160:163], v[60:63]
	v_mfma_f32_16x16x32_bf16 v[56:59], v[136:139], v[160:163], v[56:59]
	v_mfma_f32_16x16x32_bf16 v[44:47], v[128:131], v[168:171], v[44:47]
	v_mfma_f32_16x16x32_bf16 v[40:43], v[136:139], v[168:171], v[40:43]
	v_mfma_f32_16x16x32_bf16 v[28:31], v[128:131], v[176:179], v[28:31]
	v_mfma_f32_16x16x32_bf16 v[24:27], v[136:139], v[176:179], v[24:27]
	v_mfma_f32_16x16x32_bf16 v[12:15], v[128:131], v[184:187], v[12:15]
	v_mfma_f32_16x16x32_bf16 v[8:11], v[136:139], v[184:187], v[8:11]
	v_mfma_f32_16x16x32_bf16 v[60:63], v[132:135], v[164:167], v[60:63]
	v_mfma_f32_16x16x32_bf16 v[56:59], v[140:143], v[164:167], v[56:59]
	v_mfma_f32_16x16x32_bf16 v[44:47], v[132:135], v[172:175], v[44:47]
	v_mfma_f32_16x16x32_bf16 v[40:43], v[140:143], v[172:175], v[40:43]
	v_mfma_f32_16x16x32_bf16 v[28:31], v[132:135], v[180:183], v[28:31]
	v_mfma_f32_16x16x32_bf16 v[24:27], v[140:143], v[180:183], v[24:27]
	v_mfma_f32_16x16x32_bf16 v[12:15], v[132:135], v[188:191], v[12:15]
	v_mfma_f32_16x16x32_bf16 v[8:11], v[140:143], v[188:191], v[8:11]
	s_setprio 0
	s_setprio 1
	v_mfma_f32_16x16x32_bf16 v[52:55], v[144:147], v[160:163], v[52:55]
	v_mfma_f32_16x16x32_bf16 v[48:51], v[152:155], v[160:163], v[48:51]
	v_mfma_f32_16x16x32_bf16 v[36:39], v[144:147], v[168:171], v[36:39]
	v_mfma_f32_16x16x32_bf16 v[32:35], v[152:155], v[168:171], v[32:35]
	v_mfma_f32_16x16x32_bf16 v[20:23], v[144:147], v[176:179], v[20:23]
	v_mfma_f32_16x16x32_bf16 v[16:19], v[152:155], v[176:179], v[16:19]
	v_mfma_f32_16x16x32_bf16 v[4:7], v[144:147], v[184:187], v[4:7]
	v_mfma_f32_16x16x32_bf16 v[0:3], v[152:155], v[184:187], v[0:3]
	v_mfma_f32_16x16x32_bf16 v[52:55], v[148:151], v[164:167], v[52:55]
	v_mfma_f32_16x16x32_bf16 v[48:51], v[156:159], v[164:167], v[48:51]
	v_mfma_f32_16x16x32_bf16 v[36:39], v[148:151], v[172:175], v[36:39]
	v_mfma_f32_16x16x32_bf16 v[32:35], v[156:159], v[172:175], v[32:35]
	v_mfma_f32_16x16x32_bf16 v[20:23], v[148:151], v[180:183], v[20:23]
	v_mfma_f32_16x16x32_bf16 v[16:19], v[156:159], v[180:183], v[16:19]
	v_mfma_f32_16x16x32_bf16 v[4:7], v[148:151], v[188:191], v[4:7]
	v_mfma_f32_16x16x32_bf16 v[0:3], v[156:159], v[188:191], v[0:3]
	s_setprio 0
	s_barrier
	s_add_i32 s61, s61, 2
	s_add_u32 s59, s59, 0x100
	s_addc_u32 s60, s60, 0
	s_cmp_gt_u32 s61, s101
	s_mov_b64 s[2:3], s[24:25]
	s_cbranch_scc0 .LBB0_1044
	s_and_b64 vcc, exec, s[14:15]
	s_cbranch_vccz .LBB0_1047
	s_barrier

.LBB0_1112:
	s_mov_b32 s79, s76
	s_add_i32 s79, s79, -1
	s_min_u32 s79, s79, 21
	s_mov_b32 s80, s78
	s_add_i32 s79, s79, s80
	s_min_u32 s79, s79, 0x15ff
	s_lshr_b32 s80, s79, 1
	s_add_i32 s80, s80, 0xe04
	s_mul_i32 s81, s80, 0x8081
	s_lshr_b32 s81, s81, 24
	s_mul_i32 s90, s81, 0x1fe
	s_sub_i32 s80, s80, s90
	s_lshl_b32 s81, s81, 22
	s_lshl_b32 s80, s80, 13
	s_add_u32 s80, s80, s81
	s_bitcmp1_b32 s79, 0
	s_cselect_b32 s90, s66, s70
	s_cselect_b32 s91, s67, s71
	s_add_u32 s90, s90, s80
	s_addc_u32 s91, s91, 0
	global_store_dwordx4 v235, v[240:243], s[90:91] nt
	s_waitcnt vmcnt(0)
	s_barrier
	s_endpgm
